# LN phase preloads gamma/beta once; r2 units of one (seq,head) share an XCD; attention loop rescheduled
# baseline (speedup 1.0000x reference)
.LBB0_51:
	global_load_dwordx4 v[154:157], v[74:75], off
	global_load_dwordx4 v[158:161], v[76:77], off
	global_load_dwordx4 v[162:165], v[74:75], off offset:1024
	global_load_dwordx4 v[166:169], v[76:77], off offset:1024
	global_load_dwordx4 v[170:173], v[74:75], off offset:2048
	global_load_dwordx4 v[174:177], v[76:77], off offset:2048
	global_load_dwordx4 v[178:181], v[74:75], off offset:3072
	global_load_dwordx4 v[182:185], v[76:77], off offset:3072
	v_add_u32_e32 v0, 0xfffff000, v64
	v_ashrrev_i32_e32 v0, 10, v0
	v_add_u32_e32 v0, 1, v0
	v_cmp_lt_i32_e32 vcc, s33, v64
	s_mov_b32 s2, 0x1000000
	flat_load_dwordx4 v[8:11], v[86:87]
	v_cndmask_b32_e32 v4, 0, v0, vcc
	v_add_u32_e32 v0, s38, v64
	v_cmp_lt_i32_e32 vcc, s6, v0
	v_ashrrev_i32_e32 v5, 31, v4
	v_lshl_add_u64 v[88:89], v[4:5], 0, s[28:29]
	v_cndmask_b32_e32 v0, v0, v64, vcc
	v_add_u32_e32 v1, 0xfffff000, v0
	v_ashrrev_i32_e32 v1, 10, v1
	v_add_u32_e32 v1, 1, v1
	v_cmp_lt_i32_e32 vcc, s33, v0
	v_mad_u64_u32 v[4:5], s[4:5], v88, s7, v[78:79]
	s_nop 0
	v_cndmask_b32_e32 v2, 0, v1, vcc
	v_add_u32_e32 v1, s35, v64
	v_cmp_lt_i32_e32 vcc, s6, v1
	v_mad_i32_i24 v5, v89, s7, v5
	flat_load_dwordx4 v[12:15], v[4:5]
	v_cndmask_b32_e32 v40, v1, v64, vcc
	v_add_u32_e32 v1, 0xfffff000, v40
	v_ashrrev_i32_e32 v1, 10, v1
	v_add_u32_e32 v1, 1, v1
	v_cmp_lt_i32_e32 vcc, s33, v40
	v_ashrrev_i32_e32 v3, 31, v2
	v_lshl_add_u64 v[92:93], v[2:3], 0, s[28:29]
	v_cndmask_b32_e32 v42, 0, v1, vcc
	v_add_u32_e32 v1, s26, v64
	v_cmp_lt_i32_e32 vcc, s6, v1
	s_mov_b64 s[8:9], 0x1000000
	v_mad_u64_u32 v[48:49], s[4:5], v92, s7, v[78:79]
	v_cndmask_b32_e32 v20, v1, v64, vcc
	v_add_u32_e32 v1, 0xfffff000, v20
	v_ashrrev_i32_e32 v1, 10, v1
	v_add_u32_e32 v1, 1, v1
	v_cmp_lt_i32_e32 vcc, s33, v20
	v_lshlrev_b32_e32 v152, 1, v66
	v_mad_i32_i24 v49, v93, s7, v49
	v_cndmask_b32_e32 v22, 0, v1, vcc
	v_add_co_u32_e32 v6, vcc, s2, v84
	s_brev_b32 s2, 64
	s_nop 0
	v_addc_co_u32_e32 v7, vcc, 0, v85, vcc
	v_add_co_u32_e32 v24, vcc, s2, v84
	flat_load_dwordx2 v[16:17], v[6:7]
	s_nop 0
	v_addc_co_u32_e32 v25, vcc, 0, v85, vcc
	flat_load_dwordx2 v[26:27], v[24:25]
	v_lshlrev_b32_e32 v104, 1, v68
	v_mov_b32_e32 v105, v153
	v_lshlrev_b32_e32 v106, 1, v70
	v_mov_b32_e32 v107, v153
	v_lshlrev_b32_e32 v120, 1, v72
	v_mov_b32_e32 v121, v153
	v_ashrrev_i32_e32 v41, 31, v40
	v_ashrrev_i32_e32 v43, 31, v42
	v_lshlrev_b64 v[96:97], 11, v[40:41]
	v_lshl_add_u64 v[98:99], v[42:43], 0, s[28:29]
	v_lshl_add_u64 v[42:43], s[56:57], 0, v[96:97]
	v_ashrrev_i32_e32 v21, 31, v20
	v_ashrrev_i32_e32 v23, 31, v22
	s_mov_b32 s2, 0x3727c5ac
	s_waitcnt vmcnt(0) lgkmcnt(0)
	v_lshlrev_b32_e32 v18, 16, v16
	v_and_b32_e32 v19, 0xffff0000, v16
	v_lshlrev_b32_e32 v16, 16, v17
	v_and_b32_e32 v17, 0xffff0000, v17
	v_lshlrev_b32_e32 v28, 16, v26
	v_and_b32_e32 v29, 0xffff0000, v26
	v_lshlrev_b32_e32 v26, 16, v27
	v_and_b32_e32 v27, 0xffff0000, v27
	v_pk_add_f32 v[18:19], v[18:19], v[28:29]
	v_pk_add_f32 v[16:17], v[16:17], v[26:27]
	v_pk_mul_f32 v[12:13], v[12:13], v[18:19]
	v_pk_mul_f32 v[14:15], v[14:15], v[16:17]
	v_pk_fma_f32 v[8:9], v[8:9], s[42:43], v[12:13] op_sel_hi:[1,0,1]
	v_pk_fma_f32 v[10:11], v[10:11], s[42:43], v[14:15] op_sel_hi:[1,0,1]
	v_mov_b32_e32 v14, v8
	v_pk_mov_b32 v[12:13], v[8:9], v[10:11] op_sel:[1,0]
	v_mov_b32_e32 v15, v11
	v_pk_add_f32 v[12:13], v[12:13], v[14:15]
	s_nop 0
	v_add_f32_e32 v1, v12, v13
	flat_load_dwordx4 v[12:15], v[86:87] offset:1024
	flat_load_dwordx4 v[16:19], v[4:5] offset:1024
	flat_load_dwordx2 v[26:27], v[6:7] offset:512
	flat_load_dwordx2 v[32:33], v[24:25] offset:512
	v_add_f32_e32 v28, 0, v1
	v_ashrrev_i32_e32 v1, 31, v0
	v_lshlrev_b64 v[90:91], 11, v[0:1]
	v_lshlrev_b64 v[2:3], 12, v[0:1]
	s_waitcnt vmcnt(0) lgkmcnt(0)
	v_lshlrev_b32_e32 v30, 16, v26
	v_and_b32_e32 v31, 0xffff0000, v26
	v_lshlrev_b32_e32 v26, 16, v27
	v_and_b32_e32 v27, 0xffff0000, v27
	v_lshlrev_b32_e32 v34, 16, v32
	v_and_b32_e32 v35, 0xffff0000, v32
	v_lshlrev_b32_e32 v32, 16, v33
	v_and_b32_e32 v33, 0xffff0000, v33
	v_pk_add_f32 v[30:31], v[30:31], v[34:35]
	v_pk_add_f32 v[26:27], v[26:27], v[32:33]
	v_pk_mul_f32 v[16:17], v[16:17], v[30:31]
	v_pk_mul_f32 v[18:19], v[18:19], v[26:27]
	v_pk_fma_f32 v[12:13], v[12:13], s[42:43], v[16:17] op_sel_hi:[1,0,1]
	v_pk_fma_f32 v[14:15], v[14:15], s[42:43], v[18:19] op_sel_hi:[1,0,1]
	v_mov_b32_e32 v18, v12
	v_pk_mov_b32 v[16:17], v[12:13], v[14:15] op_sel:[1,0]
	v_mov_b32_e32 v19, v15
	v_pk_add_f32 v[16:17], v[16:17], v[18:19]
	s_nop 0
	v_pk_add_f32 v[30:31], v[16:17], v[16:17] op_sel:[0,1] op_sel_hi:[1,0]
	flat_load_dwordx4 v[16:19], v[86:87] offset:2048
	flat_load_dwordx4 v[32:35], v[4:5] offset:2048
	flat_load_dwordx2 v[26:27], v[6:7] offset:1024
	flat_load_dwordx2 v[38:39], v[24:25] offset:1024
	s_waitcnt vmcnt(0) lgkmcnt(0)
	v_lshlrev_b32_e32 v36, 16, v26
	v_and_b32_e32 v37, 0xffff0000, v26
	v_lshlrev_b32_e32 v44, 16, v38
	v_and_b32_e32 v45, 0xffff0000, v38
	v_lshlrev_b32_e32 v26, 16, v27
	v_and_b32_e32 v27, 0xffff0000, v27
	v_lshlrev_b32_e32 v38, 16, v39
	v_and_b32_e32 v39, 0xffff0000, v39
	v_pk_add_f32 v[36:37], v[36:37], v[44:45]
	v_pk_add_f32 v[26:27], v[26:27], v[38:39]
	v_pk_mul_f32 v[32:33], v[32:33], v[36:37]
	v_pk_mul_f32 v[26:27], v[34:35], v[26:27]
	v_pk_fma_f32 v[16:17], v[16:17], s[42:43], v[32:33] op_sel_hi:[1,0,1]
	flat_load_dwordx4 v[32:35], v[86:87] offset:3072
	flat_load_dwordx4 v[36:39], v[4:5] offset:3072
	s_nop 0
	flat_load_dwordx2 v[4:5], v[6:7] offset:1536
	v_pk_fma_f32 v[18:19], v[18:19], s[42:43], v[26:27] op_sel_hi:[1,0,1]
	flat_load_dwordx2 v[24:25], v[24:25] offset:1536
	v_add_f32_e32 v44, v16, v17
	v_add_f32_e32 v46, v18, v19
	s_waitcnt vmcnt(0) lgkmcnt(0)
	v_lshlrev_b32_e32 v6, 16, v4
	v_and_b32_e32 v7, 0xffff0000, v4
	v_lshlrev_b32_e32 v26, 16, v24
	v_and_b32_e32 v27, 0xffff0000, v24
	v_lshlrev_b32_e32 v4, 16, v5
	v_and_b32_e32 v5, 0xffff0000, v5
	v_lshlrev_b32_e32 v24, 16, v25
	v_and_b32_e32 v25, 0xffff0000, v25
	v_pk_add_f32 v[6:7], v[6:7], v[26:27]
	v_pk_add_f32 v[4:5], v[4:5], v[24:25]
	v_pk_mul_f32 v[6:7], v[36:37], v[6:7]
	v_pk_mul_f32 v[4:5], v[38:39], v[4:5]
	v_pk_fma_f32 v[24:25], v[32:33], s[42:43], v[6:7] op_sel_hi:[1,0,1]
	v_pk_fma_f32 v[26:27], v[34:35], s[42:43], v[4:5] op_sel_hi:[1,0,1]
	v_mov_b32_e32 v29, v24
	v_mov_b32_e32 v31, v25
	v_pk_add_f32 v[4:5], v[28:29], v[30:31]
	v_mov_b32_e32 v45, v26
	v_mov_b32_e32 v47, v27
	v_lshl_add_u64 v[28:29], s[56:57], 0, v[90:91]
	v_pk_add_f32 v[6:7], v[44:45], v[46:47]
	v_lshl_add_u64 v[44:45], v[28:29], 0, s[8:9]
	v_pk_add_f32 v[4:5], v[4:5], v[6:7]
	v_lshl_add_u64 v[52:53], v[28:29], 0, v[152:153]
	v_lshl_add_u64 v[34:35], v[44:45], 0, v[152:153]
	v_add_f32_e32 v122, v4, v5
	flat_load_dwordx4 v[4:7], v[48:49]
	flat_load_dwordx2 v[28:29], v[52:53]
	v_lshl_add_u64 v[32:33], v[80:81], 0, v[2:3]
	flat_load_dwordx2 v[34:35], v[34:35]
	v_lshl_add_u64 v[38:39], v[44:45], 0, v[104:105]
	flat_load_dwordx4 v[0:3], v[32:33]
	v_lshl_add_u64 v[54:55], v[44:45], 0, v[106:107]
	v_lshl_add_u64 v[44:45], v[44:45], 0, v[120:121]
	s_waitcnt vmcnt(0) lgkmcnt(0)
	v_lshlrev_b32_e32 v30, 16, v28
	v_and_b32_e32 v31, 0xffff0000, v28
	v_lshlrev_b32_e32 v28, 16, v29
	v_and_b32_e32 v29, 0xffff0000, v29
	v_lshlrev_b32_e32 v36, 16, v34
	v_and_b32_e32 v37, 0xffff0000, v34
	v_lshlrev_b32_e32 v34, 16, v35
	v_and_b32_e32 v35, 0xffff0000, v35
	v_pk_add_f32 v[30:31], v[30:31], v[36:37]
	v_pk_add_f32 v[28:29], v[28:29], v[34:35]
	v_pk_mul_f32 v[4:5], v[4:5], v[30:31]
	v_pk_mul_f32 v[6:7], v[6:7], v[28:29]
	v_pk_fma_f32 v[28:29], v[0:1], s[42:43], v[4:5] op_sel_hi:[1,0,1]
	v_pk_fma_f32 v[30:31], v[2:3], s[42:43], v[6:7] op_sel_hi:[1,0,1]
	v_mov_b32_e32 v2, v28
	v_pk_mov_b32 v[0:1], v[28:29], v[30:31] op_sel:[1,0]
	v_mov_b32_e32 v3, v31
	v_pk_add_f32 v[0:1], v[0:1], v[2:3]
	s_nop 0
	v_add_f32_e32 v0, v0, v1
	v_add_f32_e32 v46, 0, v0
	flat_load_dwordx4 v[0:3], v[32:33] offset:1024
	flat_load_dwordx4 v[4:7], v[48:49] offset:1024
	flat_load_dwordx2 v[34:35], v[52:53] offset:512
	s_waitcnt vmcnt(0) lgkmcnt(0)
	v_lshlrev_b32_e32 v36, 16, v34
	flat_load_dwordx2 v[38:39], v[38:39]
	v_and_b32_e32 v37, 0xffff0000, v34
	v_lshlrev_b32_e32 v34, 16, v35
	v_and_b32_e32 v35, 0xffff0000, v35
	s_waitcnt vmcnt(0) lgkmcnt(0)
	v_lshlrev_b32_e32 v50, 16, v38
	v_and_b32_e32 v51, 0xffff0000, v38
	v_lshlrev_b32_e32 v38, 16, v39
	v_and_b32_e32 v39, 0xffff0000, v39
	v_pk_add_f32 v[36:37], v[36:37], v[50:51]
	v_pk_add_f32 v[34:35], v[34:35], v[38:39]
	v_pk_mul_f32 v[4:5], v[4:5], v[36:37]
	v_pk_mul_f32 v[6:7], v[6:7], v[34:35]
	v_pk_fma_f32 v[38:39], v[0:1], s[42:43], v[4:5] op_sel_hi:[1,0,1]
	v_pk_fma_f32 v[60:61], v[2:3], s[42:43], v[6:7] op_sel_hi:[1,0,1]
	v_mov_b32_e32 v2, v38
	v_pk_mov_b32 v[0:1], v[38:39], v[60:61] op_sel:[1,0]
	v_mov_b32_e32 v3, v61
	v_pk_add_f32 v[0:1], v[0:1], v[2:3]
	s_nop 0
	v_pk_add_f32 v[50:51], v[0:1], v[0:1] op_sel:[0,1] op_sel_hi:[1,0]
	flat_load_dwordx4 v[0:3], v[32:33] offset:2048
	flat_load_dwordx4 v[4:7], v[48:49] offset:2048
	flat_load_dwordx2 v[34:35], v[52:53] offset:1024
	s_waitcnt vmcnt(0) lgkmcnt(0)
	v_lshlrev_b32_e32 v36, 16, v34
	flat_load_dwordx2 v[54:55], v[54:55]
	v_and_b32_e32 v37, 0xffff0000, v34
	v_lshlrev_b32_e32 v34, 16, v35
	v_and_b32_e32 v35, 0xffff0000, v35
	s_waitcnt vmcnt(0) lgkmcnt(0)
	v_lshlrev_b32_e32 v56, 16, v54
	v_and_b32_e32 v57, 0xffff0000, v54
	v_lshlrev_b32_e32 v54, 16, v55
	v_and_b32_e32 v55, 0xffff0000, v55
	v_pk_add_f32 v[34:35], v[34:35], v[54:55]
	v_pk_add_f32 v[36:37], v[36:37], v[56:57]
	v_pk_mul_f32 v[6:7], v[6:7], v[34:35]
	v_pk_mul_f32 v[4:5], v[4:5], v[36:37]
	v_pk_fma_f32 v[36:37], v[2:3], s[42:43], v[6:7] op_sel_hi:[1,0,1]
	v_pk_fma_f32 v[34:35], v[0:1], s[42:43], v[4:5] op_sel_hi:[1,0,1]
	flat_load_dwordx4 v[0:3], v[32:33] offset:3072
	flat_load_dwordx4 v[4:7], v[48:49] offset:3072
	s_nop 0
	flat_load_dwordx2 v[52:53], v[52:53] offset:1536
	v_add_f32_e32 v54, v34, v35
	flat_load_dwordx2 v[44:45], v[44:45]
	v_add_f32_e32 v56, v36, v37
	s_waitcnt vmcnt(0) lgkmcnt(0)
	v_lshlrev_b32_e32 v48, 16, v52
	v_and_b32_e32 v49, 0xffff0000, v52
	v_lshlrev_b32_e32 v58, 16, v44
	v_and_b32_e32 v59, 0xffff0000, v44
	v_lshlrev_b32_e32 v52, 16, v53
	v_and_b32_e32 v53, 0xffff0000, v53
	v_lshlrev_b32_e32 v44, 16, v45
	v_and_b32_e32 v45, 0xffff0000, v45
	v_pk_add_f32 v[48:49], v[48:49], v[58:59]
	v_pk_add_f32 v[44:45], v[52:53], v[44:45]
	v_pk_mul_f32 v[4:5], v[4:5], v[48:49]
	v_pk_mul_f32 v[6:7], v[6:7], v[44:45]
	v_pk_fma_f32 v[62:63], v[0:1], s[42:43], v[4:5] op_sel_hi:[1,0,1]
	v_pk_fma_f32 v[118:119], v[2:3], s[42:43], v[6:7] op_sel_hi:[1,0,1]
	v_mov_b32_e32 v47, v62
	v_mov_b32_e32 v51, v63
	v_pk_add_f32 v[0:1], v[46:47], v[50:51]
	v_mov_b32_e32 v55, v118
	v_mov_b32_e32 v57, v119
	v_lshl_add_u64 v[44:45], v[42:43], 0, s[8:9]
	v_mad_u64_u32 v[46:47], s[4:5], v98, s7, v[78:79]
	v_pk_add_f32 v[2:3], v[54:55], v[56:57]
	v_mad_i32_i24 v47, v99, s7, v47
	v_lshl_add_u64 v[42:43], v[42:43], 0, v[152:153]
	v_lshl_add_u64 v[52:53], v[44:45], 0, v[152:153]
	v_pk_add_f32 v[0:1], v[0:1], v[2:3]
	flat_load_dwordx4 v[4:7], v[46:47]
	flat_load_dwordx2 v[48:49], v[42:43]
	v_add_f32_e32 v126, v0, v1
	flat_load_dwordx2 v[52:53], v[52:53]
	v_lshlrev_b64 v[0:1], 12, v[40:41]
	v_lshl_add_u64 v[40:41], v[80:81], 0, v[0:1]
	flat_load_dwordx4 v[0:3], v[40:41]
	v_lshl_add_u64 v[56:57], v[44:45], 0, v[104:105]
	v_lshl_add_u64 v[102:103], v[44:45], 0, v[106:107]
	v_lshl_add_u64 v[44:45], v[44:45], 0, v[120:121]
	s_waitcnt vmcnt(0) lgkmcnt(0)
	v_lshlrev_b32_e32 v50, 16, v48
	v_and_b32_e32 v51, 0xffff0000, v48
	v_lshlrev_b32_e32 v48, 16, v49
	v_and_b32_e32 v49, 0xffff0000, v49
	v_lshlrev_b32_e32 v54, 16, v52
	v_and_b32_e32 v55, 0xffff0000, v52
	v_lshlrev_b32_e32 v52, 16, v53
	v_and_b32_e32 v53, 0xffff0000, v53
	v_pk_add_f32 v[50:51], v[50:51], v[54:55]
	v_pk_add_f32 v[48:49], v[48:49], v[52:53]
	v_pk_mul_f32 v[4:5], v[4:5], v[50:51]
	v_pk_mul_f32 v[6:7], v[6:7], v[48:49]
	v_pk_fma_f32 v[50:51], v[0:1], s[42:43], v[4:5] op_sel_hi:[1,0,1]
	v_pk_fma_f32 v[52:53], v[2:3], s[42:43], v[6:7] op_sel_hi:[1,0,1]
	v_mov_b32_e32 v2, v50
	v_pk_mov_b32 v[0:1], v[50:51], v[52:53] op_sel:[1,0]
	v_mov_b32_e32 v3, v53
	v_pk_add_f32 v[0:1], v[0:1], v[2:3]
	s_nop 0
	v_add_f32_e32 v0, v0, v1
	v_add_f32_e32 v94, 0, v0
	flat_load_dwordx4 v[0:3], v[40:41] offset:1024
	flat_load_dwordx4 v[4:7], v[46:47] offset:1024
	flat_load_dwordx2 v[48:49], v[42:43] offset:512
	s_waitcnt vmcnt(0) lgkmcnt(0)
	v_lshlrev_b32_e32 v54, 16, v48
	flat_load_dwordx2 v[56:57], v[56:57]
	v_and_b32_e32 v55, 0xffff0000, v48
	v_lshlrev_b32_e32 v48, 16, v49
	v_and_b32_e32 v49, 0xffff0000, v49
	s_waitcnt vmcnt(0) lgkmcnt(0)
	v_lshlrev_b32_e32 v58, 16, v56
	v_and_b32_e32 v59, 0xffff0000, v56
	v_lshlrev_b32_e32 v56, 16, v57
	v_and_b32_e32 v57, 0xffff0000, v57
	v_pk_add_f32 v[54:55], v[54:55], v[58:59]
	v_pk_add_f32 v[48:49], v[48:49], v[56:57]
	v_pk_mul_f32 v[4:5], v[4:5], v[54:55]
	v_pk_mul_f32 v[6:7], v[6:7], v[48:49]
	v_pk_fma_f32 v[56:57], v[0:1], s[42:43], v[4:5] op_sel_hi:[1,0,1]
	v_pk_fma_f32 v[58:59], v[2:3], s[42:43], v[6:7] op_sel_hi:[1,0,1]
	v_mov_b32_e32 v2, v56
	v_pk_mov_b32 v[0:1], v[56:57], v[58:59] op_sel:[1,0]
	v_mov_b32_e32 v3, v59
	v_pk_add_f32 v[0:1], v[0:1], v[2:3]
	s_nop 0
	v_pk_add_f32 v[100:101], v[0:1], v[0:1] op_sel:[0,1] op_sel_hi:[1,0]
	flat_load_dwordx4 v[0:3], v[40:41] offset:2048
	flat_load_dwordx4 v[4:7], v[46:47] offset:2048
	flat_load_dwordx2 v[48:49], v[42:43] offset:1024
	s_waitcnt vmcnt(0) lgkmcnt(0)
	v_lshlrev_b32_e32 v54, 16, v48
	flat_load_dwordx2 v[102:103], v[102:103]
	v_and_b32_e32 v55, 0xffff0000, v48
	v_lshlrev_b32_e32 v48, 16, v49
	v_and_b32_e32 v49, 0xffff0000, v49
	s_waitcnt vmcnt(0) lgkmcnt(0)
	v_lshlrev_b32_e32 v108, 16, v102
	v_and_b32_e32 v109, 0xffff0000, v102
	v_lshlrev_b32_e32 v102, 16, v103
	v_and_b32_e32 v103, 0xffff0000, v103
	v_pk_add_f32 v[48:49], v[48:49], v[102:103]
	v_pk_add_f32 v[54:55], v[54:55], v[108:109]
	v_pk_mul_f32 v[6:7], v[6:7], v[48:49]
	v_pk_mul_f32 v[4:5], v[4:5], v[54:55]
	v_pk_fma_f32 v[116:117], v[2:3], s[42:43], v[6:7] op_sel_hi:[1,0,1]
	v_pk_fma_f32 v[54:55], v[0:1], s[42:43], v[4:5] op_sel_hi:[1,0,1]
	flat_load_dwordx4 v[0:3], v[40:41] offset:3072
	flat_load_dwordx4 v[4:7], v[46:47] offset:3072
	s_nop 0
	flat_load_dwordx2 v[42:43], v[42:43] offset:1536
	v_add_f32_e32 v102, v54, v55
	flat_load_dwordx2 v[44:45], v[44:45]
	v_add_f32_e32 v108, v116, v117
	s_waitcnt vmcnt(0) lgkmcnt(0)
	v_lshlrev_b32_e32 v46, 16, v42
	v_and_b32_e32 v47, 0xffff0000, v42
	v_lshlrev_b32_e32 v42, 16, v43
	v_and_b32_e32 v43, 0xffff0000, v43
	v_lshlrev_b32_e32 v48, 16, v44
	v_and_b32_e32 v49, 0xffff0000, v44
	v_lshlrev_b32_e32 v44, 16, v45
	v_and_b32_e32 v45, 0xffff0000, v45
	v_pk_add_f32 v[42:43], v[42:43], v[44:45]
	v_pk_add_f32 v[44:45], v[46:47], v[48:49]
	v_pk_mul_f32 v[6:7], v[6:7], v[42:43]
	v_pk_mul_f32 v[4:5], v[4:5], v[44:45]
	v_pk_fma_f32 v[48:49], v[2:3], s[42:43], v[6:7] op_sel_hi:[1,0,1]
	v_pk_fma_f32 v[46:47], v[0:1], s[42:43], v[4:5] op_sel_hi:[1,0,1]
	v_mov_b32_e32 v103, v48
	v_mov_b32_e32 v95, v46
	v_mov_b32_e32 v101, v47
	v_mov_b32_e32 v109, v49
	v_pk_add_f32 v[0:1], v[94:95], v[100:101]
	v_pk_add_f32 v[2:3], v[102:103], v[108:109]
	v_lshlrev_b64 v[94:95], 11, v[20:21]
	v_pk_add_f32 v[0:1], v[0:1], v[2:3]
	v_lshl_add_u64 v[100:101], v[22:23], 0, s[28:29]
	v_add_f32_e32 v125, v0, v1
	v_lshlrev_b64 v[0:1], 12, v[20:21]
	v_lshl_add_u64 v[20:21], s[56:57], 0, v[94:95]
	v_lshl_add_u64 v[22:23], v[20:21], 0, s[8:9]
	v_mad_u64_u32 v[128:129], s[4:5], v100, s7, v[78:79]
	v_mad_i32_i24 v129, v101, s7, v129
	v_lshl_add_u64 v[20:21], v[20:21], 0, v[152:153]
	v_lshl_add_u64 v[108:109], v[22:23], 0, v[152:153]
	flat_load_dwordx4 v[4:7], v[128:129]
	flat_load_dwordx2 v[42:43], v[20:21]
	v_lshl_add_u64 v[102:103], v[80:81], 0, v[0:1]
	flat_load_dwordx2 v[108:109], v[108:109]
	v_lshl_add_u64 v[104:105], v[22:23], 0, v[104:105]
	flat_load_dwordx4 v[0:3], v[102:103]
	v_lshl_add_u64 v[106:107], v[22:23], 0, v[106:107]
	v_lshl_add_u64 v[22:23], v[22:23], 0, v[120:121]
	v_readlane_b32 s4, v254, 33
	v_readlane_b32 s5, v254, 34
	s_waitcnt vmcnt(0) lgkmcnt(0)
	v_lshlrev_b32_e32 v44, 16, v42
	v_and_b32_e32 v45, 0xffff0000, v42
	v_lshlrev_b32_e32 v42, 16, v43
	v_and_b32_e32 v43, 0xffff0000, v43
	v_lshlrev_b32_e32 v110, 16, v108
	v_and_b32_e32 v111, 0xffff0000, v108
	v_lshlrev_b32_e32 v108, 16, v109
	v_and_b32_e32 v109, 0xffff0000, v109
	v_pk_add_f32 v[44:45], v[44:45], v[110:111]
	v_pk_add_f32 v[42:43], v[42:43], v[108:109]
	v_pk_mul_f32 v[4:5], v[4:5], v[44:45]
	v_pk_mul_f32 v[6:7], v[6:7], v[42:43]
	v_pk_fma_f32 v[44:45], v[0:1], s[42:43], v[4:5] op_sel_hi:[1,0,1]
	v_pk_fma_f32 v[114:115], v[2:3], s[42:43], v[6:7] op_sel_hi:[1,0,1]
	v_mov_b32_e32 v2, v44
	v_pk_mov_b32 v[0:1], v[44:45], v[114:115] op_sel:[1,0]
	v_mov_b32_e32 v3, v115
	v_pk_add_f32 v[0:1], v[0:1], v[2:3]
	s_nop 0
	v_add_f32_e32 v0, v0, v1
	v_add_f32_e32 v130, 0, v0
	flat_load_dwordx4 v[0:3], v[102:103] offset:1024
	flat_load_dwordx4 v[4:7], v[128:129] offset:1024
	flat_load_dwordx2 v[42:43], v[20:21] offset:512
	s_waitcnt vmcnt(0) lgkmcnt(0)
	v_lshlrev_b32_e32 v108, 16, v42
	flat_load_dwordx2 v[104:105], v[104:105]
	v_and_b32_e32 v109, 0xffff0000, v42
	v_lshlrev_b32_e32 v42, 16, v43
	v_and_b32_e32 v43, 0xffff0000, v43
	s_waitcnt vmcnt(0) lgkmcnt(0)
	v_lshlrev_b32_e32 v110, 16, v104
	v_and_b32_e32 v111, 0xffff0000, v104
	v_lshlrev_b32_e32 v104, 16, v105
	v_and_b32_e32 v105, 0xffff0000, v105
	v_pk_add_f32 v[108:109], v[108:109], v[110:111]
	v_pk_add_f32 v[42:43], v[42:43], v[104:105]
	v_pk_mul_f32 v[4:5], v[4:5], v[108:109]
	v_pk_mul_f32 v[6:7], v[6:7], v[42:43]
	v_pk_fma_f32 v[42:43], v[0:1], s[42:43], v[4:5] op_sel_hi:[1,0,1]
	v_pk_fma_f32 v[112:113], v[2:3], s[42:43], v[6:7] op_sel_hi:[1,0,1]
	v_mov_b32_e32 v2, v42
	v_pk_mov_b32 v[0:1], v[42:43], v[112:113] op_sel:[1,0]
	v_mov_b32_e32 v3, v113
	v_pk_add_f32 v[0:1], v[0:1], v[2:3]
	s_nop 0
	v_pk_add_f32 v[132:133], v[0:1], v[0:1] op_sel:[0,1] op_sel_hi:[1,0]
	flat_load_dwordx4 v[0:3], v[102:103] offset:2048
	flat_load_dwordx4 v[4:7], v[128:129] offset:2048
	flat_load_dwordx2 v[104:105], v[20:21] offset:1024
	s_waitcnt vmcnt(0) lgkmcnt(0)
	v_lshlrev_b32_e32 v108, 16, v104
	flat_load_dwordx2 v[106:107], v[106:107]
	v_and_b32_e32 v109, 0xffff0000, v104
	v_lshlrev_b32_e32 v104, 16, v105
	v_and_b32_e32 v105, 0xffff0000, v105
	s_waitcnt vmcnt(0) lgkmcnt(0)
	v_lshlrev_b32_e32 v110, 16, v106
	v_and_b32_e32 v111, 0xffff0000, v106
	v_lshlrev_b32_e32 v106, 16, v107
	v_and_b32_e32 v107, 0xffff0000, v107
	v_pk_add_f32 v[104:105], v[104:105], v[106:107]
	v_pk_add_f32 v[106:107], v[108:109], v[110:111]
	v_pk_mul_f32 v[6:7], v[6:7], v[104:105]
	v_pk_mul_f32 v[4:5], v[4:5], v[106:107]
	v_pk_fma_f32 v[110:111], v[2:3], s[42:43], v[6:7] op_sel_hi:[1,0,1]
	v_pk_fma_f32 v[108:109], v[0:1], s[42:43], v[4:5] op_sel_hi:[1,0,1]
	flat_load_dwordx4 v[0:3], v[102:103] offset:3072
	flat_load_dwordx4 v[4:7], v[128:129] offset:3072
	s_nop 0
	flat_load_dwordx2 v[20:21], v[20:21] offset:1536
	v_add_f32_e32 v134, v108, v109
	flat_load_dwordx2 v[22:23], v[22:23]
	v_add_f32_e32 v136, v110, v111
	s_waitcnt vmcnt(0) lgkmcnt(0)
	v_lshlrev_b32_e32 v104, 16, v20
	v_and_b32_e32 v105, 0xffff0000, v20
	v_lshlrev_b32_e32 v20, 16, v21
	v_and_b32_e32 v21, 0xffff0000, v21
	v_lshlrev_b32_e32 v106, 16, v22
	v_and_b32_e32 v107, 0xffff0000, v22
	v_lshlrev_b32_e32 v22, 16, v23
	v_and_b32_e32 v23, 0xffff0000, v23
	v_pk_add_f32 v[20:21], v[20:21], v[22:23]
	v_pk_add_f32 v[22:23], v[104:105], v[106:107]
	v_pk_mul_f32 v[6:7], v[6:7], v[20:21]
	v_pk_mul_f32 v[4:5], v[4:5], v[22:23]
	v_pk_fma_f32 v[106:107], v[2:3], s[42:43], v[6:7] op_sel_hi:[1,0,1]
	v_pk_fma_f32 v[104:105], v[0:1], s[42:43], v[4:5] op_sel_hi:[1,0,1]
	v_mov_b32_e32 v135, v106
	v_mov_b32_e32 v131, v104
	v_mov_b32_e32 v133, v105
	v_mov_b32_e32 v137, v107
	v_pk_add_f32 v[0:1], v[130:131], v[132:133]
	v_pk_add_f32 v[2:3], v[134:135], v[136:137]
	ds_bpermute_b32 v22, v67, v126
	v_pk_add_f32 v[0:1], v[0:1], v[2:3]
	s_waitcnt lgkmcnt(0)
	v_add_f32_e32 v22, v126, v22
	v_add_f32_e32 v65, v0, v1
	ds_bpermute_b32 v0, v67, v122
	ds_bpermute_b32 v23, v69, v22
	s_waitcnt lgkmcnt(1)
	v_add_f32_e32 v0, v122, v0
	ds_bpermute_b32 v1, v69, v0
	s_waitcnt lgkmcnt(1)
	v_add_f32_e32 v22, v22, v23
	ds_bpermute_b32 v23, v71, v22
	s_waitcnt lgkmcnt(1)
	v_add_f32_e32 v0, v0, v1
	ds_bpermute_b32 v1, v71, v0
	s_waitcnt lgkmcnt(1)
	v_add_f32_e32 v22, v22, v23
	ds_bpermute_b32 v23, v73, v22
	s_waitcnt lgkmcnt(1)
	v_add_f32_e32 v0, v0, v1
	ds_bpermute_b32 v1, v73, v0
	s_waitcnt lgkmcnt(1)
	v_add_f32_e32 v22, v22, v23
	ds_bpermute_b32 v23, v123, v22
	s_waitcnt lgkmcnt(1)
	v_add_f32_e32 v0, v0, v1
	ds_bpermute_b32 v1, v123, v0
	s_waitcnt lgkmcnt(1)
	v_add_f32_e32 v22, v22, v23
	ds_bpermute_b32 v23, v124, v22
	s_waitcnt lgkmcnt(1)
	v_add_f32_e32 v0, v0, v1
	ds_bpermute_b32 v1, v124, v0
	s_waitcnt lgkmcnt(1)
	v_add_f32_e32 v122, v22, v23
	v_fmamk_f32 v29, v122, 0xba800000, v29
	v_fmac_f32_e32 v28, 0xba800000, v122
	v_fmamk_f32 v31, v122, 0xba800000, v31
	s_waitcnt lgkmcnt(0)
	v_add_f32_e32 v20, v0, v1
	v_fmamk_f32 v9, v20, 0xba800000, v9
	v_fmac_f32_e32 v8, 0xba800000, v20
	v_fmamk_f32 v11, v20, 0xba800000, v11
	v_fmac_f32_e32 v10, 0xba800000, v20
	v_pk_mul_f32 v[0:1], v[10:11], v[10:11]
	v_pk_mul_f32 v[2:3], v[8:9], v[8:9]
	v_fmamk_f32 v13, v20, 0xba800000, v13
	v_pk_mov_b32 v[4:5], v[2:3], v[0:1] op_sel:[1,0]
	v_mov_b32_e32 v3, v1
	v_pk_add_f32 v[0:1], v[4:5], v[2:3]
	v_fmac_f32_e32 v12, 0xba800000, v20
	v_fmamk_f32 v15, v20, 0xba800000, v15
	v_fmac_f32_e32 v14, 0xba800000, v20
	v_pk_add_f32 v[0:1], v[0:1], v[0:1] op_sel_hi:[0,1]
	v_pk_mul_f32 v[2:3], v[14:15], v[14:15]
	v_pk_mul_f32 v[4:5], v[12:13], v[12:13]
	v_fmac_f32_e32 v16, 0xba800000, v20
	v_pk_mov_b32 v[6:7], v[4:5], v[2:3] op_sel:[1,0]
	v_mov_b32_e32 v5, v3
	v_fmamk_f32 v17, v20, 0xba800000, v17
	v_fmac_f32_e32 v18, 0xba800000, v20
	v_mul_f32_e32 v0, v16, v16
	v_pk_add_f32 v[2:3], v[6:7], v[4:5]
	v_fmamk_f32 v19, v20, 0xba800000, v19
	v_pk_fma_f32 v[4:5], v[16:17], v[16:17], v[0:1] op_sel_hi:[1,1,0]
	v_mul_f32_e32 v0, v18, v18
	v_pk_add_f32 v[2:3], v[2:3], v[2:3] op_sel_hi:[0,1]
	v_pk_fma_f32 v[6:7], v[18:19], v[18:19], v[0:1] op_sel_hi:[1,1,0]
	v_fmamk_f32 v27, v20, 0xba800000, v27
	v_fmac_f32_e32 v26, 0xba800000, v20
	v_fmamk_f32 v25, v20, 0xba800000, v25
	v_fmac_f32_e32 v24, 0xba800000, v20
	v_mul_f32_e32 v4, v24, v24
	v_mul_f32_e32 v6, v25, v25
	v_mul_f32_e32 v0, v26, v26
	v_mul_f32_e32 v2, v27, v27
	v_pk_add_f32 v[4:5], v[4:5], v[6:7]
	v_pk_add_f32 v[0:1], v[0:1], v[2:3]
	v_fmac_f32_e32 v30, 0xba800000, v122
	v_pk_add_f32 v[20:21], v[4:5], v[0:1]
	v_mov_b64_e32 v[0:1], v[154:155]
	v_mov_b64_e32 v[2:3], v[156:157]
	v_mov_b64_e32 v[4:5], v[158:159]
	v_mov_b64_e32 v[6:7], v[160:161]
	v_pk_mul_f32 v[22:23], v[30:31], v[30:31]
	v_pk_mul_f32 v[120:121], v[28:29], v[28:29]
	v_fmamk_f32 v39, v122, 0xba800000, v39
	v_pk_mov_b32 v[126:127], v[120:121], v[22:23] op_sel:[1,0]
	v_mov_b32_e32 v121, v23
	v_pk_add_f32 v[22:23], v[126:127], v[120:121]
	v_fmac_f32_e32 v38, 0xba800000, v122
	v_fmamk_f32 v61, v122, 0xba800000, v61
	v_fmac_f32_e32 v60, 0xba800000, v122
	v_pk_add_f32 v[22:23], v[22:23], v[22:23] op_sel_hi:[0,1]
	v_pk_mul_f32 v[120:121], v[60:61], v[60:61]
	v_pk_mul_f32 v[126:127], v[38:39], v[38:39]
	v_fmac_f32_e32 v34, 0xba800000, v122
	v_pk_mov_b32 v[128:129], v[126:127], v[120:121] op_sel:[1,0]
	v_mov_b32_e32 v127, v121
	v_fmamk_f32 v35, v122, 0xba800000, v35
	v_fmac_f32_e32 v36, 0xba800000, v122
	v_mul_f32_e32 v22, v34, v34
	v_pk_add_f32 v[120:121], v[128:129], v[126:127]
	v_fmamk_f32 v37, v122, 0xba800000, v37
	v_pk_fma_f32 v[126:127], v[34:35], v[34:35], v[22:23] op_sel_hi:[1,1,0]
	v_mul_f32_e32 v22, v36, v36
	v_pk_add_f32 v[120:121], v[120:121], v[120:121] op_sel_hi:[0,1]
	v_pk_fma_f32 v[128:129], v[36:37], v[36:37], v[22:23] op_sel_hi:[1,1,0]
	v_fmamk_f32 v119, v122, 0xba800000, v119
	v_fmac_f32_e32 v118, 0xba800000, v122
	v_fmamk_f32 v63, v122, 0xba800000, v63
	v_fmac_f32_e32 v62, 0xba800000, v122
	v_mul_f32_e32 v126, v62, v62
	v_mul_f32_e32 v128, v63, v63
	v_mul_f32_e32 v22, v118, v118
	v_mul_f32_e32 v120, v119, v119
	v_pk_add_f32 v[126:127], v[126:127], v[128:129]
	v_pk_add_f32 v[22:23], v[22:23], v[120:121]
	v_mov_b32_e32 v121, v20
	v_pk_add_f32 v[22:23], v[126:127], v[22:23]
	s_nop 0
	v_mov_b32_e32 v120, v22
	v_mov_b32_e32 v20, v23
	v_pk_add_f32 v[20:21], v[120:121], v[20:21]
	ds_bpermute_b32 v23, v67, v21
	ds_bpermute_b32 v22, v67, v20
	v_mov_b64_e32 v[120:121], s[2:3]
	s_mov_b32 s2, 0x3a800000
	s_waitcnt lgkmcnt(0)
	v_pk_add_f32 v[20:21], v[20:21], v[22:23]
	ds_bpermute_b32 v23, v69, v21
	ds_bpermute_b32 v22, v69, v20
	s_waitcnt lgkmcnt(0)
	v_pk_add_f32 v[20:21], v[20:21], v[22:23]
	ds_bpermute_b32 v23, v71, v21
	ds_bpermute_b32 v22, v71, v20
	s_waitcnt lgkmcnt(0)
	v_pk_add_f32 v[20:21], v[20:21], v[22:23]
	ds_bpermute_b32 v23, v73, v21
	ds_bpermute_b32 v22, v73, v20
	s_waitcnt lgkmcnt(0)
	v_pk_add_f32 v[20:21], v[20:21], v[22:23]
	ds_bpermute_b32 v23, v123, v21
	ds_bpermute_b32 v22, v123, v20
	s_waitcnt lgkmcnt(0)
	v_pk_add_f32 v[20:21], v[20:21], v[22:23]
	ds_bpermute_b32 v23, v124, v21
	ds_bpermute_b32 v22, v124, v20
	s_waitcnt lgkmcnt(0)
	v_pk_add_f32 v[20:21], v[20:21], v[22:23]
	s_nop 0
	v_pk_fma_f32 v[126:127], v[20:21], s[2:3], v[120:121] op_sel_hi:[1,0,0]
	s_nop 0
	v_mul_f32_e32 v20, 0x4b800000, v127
	v_cmp_gt_f32_e64 s[8:9], s68, v127
	v_cmp_gt_f32_e32 vcc, s68, v126
	s_nop 0
	v_cndmask_b32_e64 v20, v127, v20, s[8:9]
	v_rsq_f32_e32 v20, v20
	s_nop 0
	v_mul_f32_e32 v21, 0x45800000, v20
	v_cndmask_b32_e64 v122, v20, v21, s[8:9]
	v_pk_mul_f32 v[8:9], v[8:9], v[122:123] op_sel_hi:[1,0]
	v_pk_mul_f32 v[10:11], v[10:11], v[122:123] op_sel_hi:[1,0]
	v_pk_fma_f32 v[20:21], v[0:1], v[8:9], v[4:5]
	v_pk_fma_f32 v[22:23], v[2:3], v[10:11], v[6:7]
	flat_store_dwordx4 v[86:87], v[20:23]
	v_mov_b64_e32 v[0:1], v[162:163]
	v_mov_b64_e32 v[2:3], v[164:165]
	v_mov_b64_e32 v[4:5], v[166:167]
	v_mov_b64_e32 v[6:7], v[168:169]
	v_pk_mul_f32 v[8:9], v[14:15], v[122:123] op_sel_hi:[1,0]
	v_pk_mul_f32 v[10:11], v[12:13], v[122:123] op_sel_hi:[1,0]
	v_pk_fma_f32 v[14:15], v[2:3], v[8:9], v[6:7]
	v_pk_fma_f32 v[12:13], v[0:1], v[10:11], v[4:5]
	flat_store_dwordx4 v[86:87], v[12:15] offset:1024
	v_mov_b64_e32 v[0:1], v[170:171]
	v_mov_b64_e32 v[2:3], v[172:173]
	v_mov_b64_e32 v[4:5], v[174:175]
	v_mov_b64_e32 v[6:7], v[176:177]
	v_pk_mul_f32 v[8:9], v[18:19], v[122:123] op_sel_hi:[1,0]
	v_pk_mul_f32 v[10:11], v[16:17], v[122:123] op_sel_hi:[1,0]
	v_pk_mul_f32 v[18:19], v[24:25], v[122:123] op_sel_hi:[1,0]
	v_pk_mul_f32 v[16:17], v[26:27], v[122:123] op_sel_hi:[1,0]
	v_pk_fma_f32 v[4:5], v[0:1], v[10:11], v[4:5]
	v_pk_fma_f32 v[6:7], v[2:3], v[8:9], v[6:7]
	flat_store_dwordx4 v[86:87], v[4:7] offset:2048
	v_mov_b64_e32 v[0:1], v[178:179]
	v_mov_b64_e32 v[2:3], v[180:181]
	v_mov_b64_e32 v[8:9], v[182:183]
	v_mov_b64_e32 v[10:11], v[184:185]
	v_pk_fma_f32 v[0:1], v[0:1], v[18:19], v[8:9]
	v_mul_f32_e32 v8, 0x4b800000, v126
	v_cndmask_b32_e32 v8, v126, v8, vcc
	v_rsq_f32_e32 v8, v8
	v_pk_fma_f32 v[2:3], v[2:3], v[16:17], v[10:11]
	flat_store_dwordx4 v[86:87], v[0:3] offset:3072
	v_mul_f32_e32 v9, 0x45800000, v8
	v_cndmask_b32_e32 v122, v8, v9, vcc
	v_mov_b64_e32 v[8:9], v[154:155]
	v_mov_b64_e32 v[10:11], v[156:157]
	v_mov_b64_e32 v[16:17], v[158:159]
	v_mov_b64_e32 v[18:19], v[160:161]
	v_pk_mul_f32 v[24:25], v[30:31], v[122:123] op_sel_hi:[1,0]
	v_pk_mul_f32 v[26:27], v[28:29], v[122:123] op_sel_hi:[1,0]
	v_pk_mul_f32 v[30:31], v[60:61], v[122:123] op_sel_hi:[1,0]
	v_pk_mul_f32 v[28:29], v[38:39], v[122:123] op_sel_hi:[1,0]
	v_pk_mul_f32 v[36:37], v[36:37], v[122:123] op_sel_hi:[1,0]
	v_pk_mul_f32 v[34:35], v[34:35], v[122:123] op_sel_hi:[1,0]
	v_pk_mul_f32 v[38:39], v[118:119], v[122:123] op_sel_hi:[1,0]
	v_pk_mul_f32 v[60:61], v[62:63], v[122:123] op_sel_hi:[1,0]
	ds_bpermute_b32 v62, v67, v65
	s_waitcnt lgkmcnt(0)
	v_add_f32_e32 v62, v65, v62
	ds_bpermute_b32 v63, v69, v62
	s_waitcnt lgkmcnt(0)
	v_add_f32_e32 v62, v62, v63
	ds_bpermute_b32 v63, v71, v62
	s_waitcnt lgkmcnt(0)
	v_add_f32_e32 v62, v62, v63
	ds_bpermute_b32 v63, v73, v62
	s_waitcnt lgkmcnt(0)
	v_add_f32_e32 v62, v62, v63
	ds_bpermute_b32 v63, v123, v62
	s_waitcnt lgkmcnt(0)
	v_add_f32_e32 v62, v62, v63
	ds_bpermute_b32 v63, v124, v62
	s_waitcnt lgkmcnt(0)
	v_add_f32_e32 v65, v62, v63
	v_fmamk_f32 v45, v65, 0xba800000, v45
	v_fmac_f32_e32 v44, 0xba800000, v65
	v_fmamk_f32 v115, v65, 0xba800000, v115
	v_fmac_f32_e32 v114, 0xba800000, v65
	v_pk_mul_f32 v[62:63], v[114:115], v[114:115]
	v_pk_mul_f32 v[118:119], v[44:45], v[44:45]
	v_fmamk_f32 v43, v65, 0xba800000, v43
	v_pk_mov_b32 v[126:127], v[118:119], v[62:63] op_sel:[1,0]
	v_mov_b32_e32 v119, v63
	v_pk_add_f32 v[62:63], v[126:127], v[118:119]
	v_fmac_f32_e32 v42, 0xba800000, v65
	v_fmamk_f32 v113, v65, 0xba800000, v113
	v_fmac_f32_e32 v112, 0xba800000, v65
	v_pk_add_f32 v[62:63], v[62:63], v[62:63] op_sel_hi:[0,1]
	v_pk_mul_f32 v[118:119], v[112:113], v[112:113]
	v_pk_mul_f32 v[126:127], v[42:43], v[42:43]
	v_fmac_f32_e32 v108, 0xba800000, v65
	v_pk_mov_b32 v[128:129], v[126:127], v[118:119] op_sel:[1,0]
	v_mov_b32_e32 v127, v119
	v_fmamk_f32 v109, v65, 0xba800000, v109
	v_fmac_f32_e32 v110, 0xba800000, v65
	v_mul_f32_e32 v62, v108, v108
	v_pk_add_f32 v[118:119], v[128:129], v[126:127]
	v_fmamk_f32 v111, v65, 0xba800000, v111
	v_pk_fma_f32 v[126:127], v[108:109], v[108:109], v[62:63] op_sel_hi:[1,1,0]
	v_mul_f32_e32 v62, v110, v110
	v_pk_add_f32 v[118:119], v[118:119], v[118:119] op_sel_hi:[0,1]
	v_pk_fma_f32 v[128:129], v[110:111], v[110:111], v[62:63] op_sel_hi:[1,1,0]
	v_fmamk_f32 v107, v65, 0xba800000, v107
	v_fmac_f32_e32 v106, 0xba800000, v65
	v_fmamk_f32 v105, v65, 0xba800000, v105
	v_fmac_f32_e32 v104, 0xba800000, v65
	v_mul_f32_e32 v126, v104, v104
	v_mul_f32_e32 v128, v105, v105
	v_mul_f32_e32 v62, v106, v106
	v_pk_fma_f32 v[8:9], v[8:9], v[26:27], v[16:17]
	v_pk_fma_f32 v[10:11], v[10:11], v[24:25], v[18:19]
	flat_store_dwordx4 v[32:33], v[8:11]
	v_mov_b64_e32 v[16:17], v[162:163]
	v_mov_b64_e32 v[18:19], v[164:165]
	v_mov_b64_e32 v[24:25], v[166:167]
	v_mov_b64_e32 v[26:27], v[168:169]
	v_mul_f32_e32 v118, v107, v107
	v_pk_add_f32 v[126:127], v[126:127], v[128:129]
	v_pk_add_f32 v[62:63], v[62:63], v[118:119]
	v_pk_fma_f32 v[28:29], v[16:17], v[28:29], v[24:25]
	v_pk_fma_f32 v[30:31], v[18:19], v[30:31], v[26:27]
	flat_store_dwordx4 v[32:33], v[28:31] offset:1024
	v_mov_b64_e32 v[16:17], v[170:171]
	v_mov_b64_e32 v[18:19], v[172:173]
	v_mov_b64_e32 v[24:25], v[174:175]
	v_mov_b64_e32 v[26:27], v[176:177]
	v_pk_add_f32 v[62:63], v[126:127], v[62:63]
	v_pk_fma_f32 v[24:25], v[16:17], v[34:35], v[24:25]
	v_pk_fma_f32 v[26:27], v[18:19], v[36:37], v[26:27]
	flat_store_dwordx4 v[32:33], v[24:27] offset:2048
	v_mov_b64_e32 v[16:17], v[178:179]
	v_mov_b64_e32 v[18:19], v[180:181]
	v_mov_b64_e32 v[34:35], v[182:183]
	v_mov_b64_e32 v[36:37], v[184:185]
	v_mov_b32_e32 v118, v62
	v_pk_fma_f32 v[16:17], v[16:17], v[60:61], v[34:35]
	v_pk_fma_f32 v[18:19], v[18:19], v[38:39], v[36:37]
	flat_store_dwordx4 v[32:33], v[16:19] offset:3072
	ds_bpermute_b32 v32, v67, v125
	s_waitcnt lgkmcnt(0)
	v_add_f32_e32 v32, v125, v32
	ds_bpermute_b32 v33, v69, v32
	s_waitcnt lgkmcnt(0)
	v_add_f32_e32 v32, v32, v33
	ds_bpermute_b32 v33, v71, v32
	s_waitcnt lgkmcnt(0)
	v_add_f32_e32 v32, v32, v33
	ds_bpermute_b32 v33, v73, v32
	s_waitcnt lgkmcnt(0)
	v_add_f32_e32 v32, v32, v33
	ds_bpermute_b32 v33, v123, v32
	s_waitcnt lgkmcnt(0)
	v_add_f32_e32 v32, v32, v33
	ds_bpermute_b32 v33, v124, v32
	s_waitcnt lgkmcnt(0)
	v_add_f32_e32 v60, v32, v33
	v_fmamk_f32 v51, v60, 0xba800000, v51
	v_fmac_f32_e32 v50, 0xba800000, v60
	v_fmamk_f32 v53, v60, 0xba800000, v53
	v_fmac_f32_e32 v52, 0xba800000, v60
	v_pk_mul_f32 v[32:33], v[52:53], v[52:53]
	v_pk_mul_f32 v[34:35], v[50:51], v[50:51]
	v_fmamk_f32 v57, v60, 0xba800000, v57
	v_pk_mov_b32 v[36:37], v[34:35], v[32:33] op_sel:[1,0]
	v_mov_b32_e32 v35, v33
	v_pk_add_f32 v[32:33], v[36:37], v[34:35]
	v_fmac_f32_e32 v56, 0xba800000, v60
	v_fmamk_f32 v59, v60, 0xba800000, v59
	v_fmac_f32_e32 v58, 0xba800000, v60
	v_pk_add_f32 v[32:33], v[32:33], v[32:33] op_sel_hi:[0,1]
	v_pk_mul_f32 v[34:35], v[58:59], v[58:59]
	v_pk_mul_f32 v[36:37], v[56:57], v[56:57]
	v_fmac_f32_e32 v54, 0xba800000, v60
	v_pk_mov_b32 v[38:39], v[36:37], v[34:35] op_sel:[1,0]
	v_mov_b32_e32 v37, v35
	v_fmamk_f32 v55, v60, 0xba800000, v55
	v_fmac_f32_e32 v116, 0xba800000, v60
	v_mul_f32_e32 v32, v54, v54
	v_pk_add_f32 v[34:35], v[38:39], v[36:37]
	v_fmamk_f32 v117, v60, 0xba800000, v117
	v_pk_fma_f32 v[36:37], v[54:55], v[54:55], v[32:33] op_sel_hi:[1,1,0]
	v_mul_f32_e32 v32, v116, v116
	v_pk_add_f32 v[34:35], v[34:35], v[34:35] op_sel_hi:[0,1]
	v_pk_fma_f32 v[38:39], v[116:117], v[116:117], v[32:33] op_sel_hi:[1,1,0]
	v_fmamk_f32 v49, v60, 0xba800000, v49
	v_fmac_f32_e32 v48, 0xba800000, v60
	v_fmamk_f32 v47, v60, 0xba800000, v47
	v_fmac_f32_e32 v46, 0xba800000, v60
	v_mul_f32_e32 v36, v46, v46
	v_mul_f32_e32 v38, v47, v47
	v_mul_f32_e32 v32, v48, v48
	v_mul_f32_e32 v34, v49, v49
	v_pk_add_f32 v[36:37], v[36:37], v[38:39]
	v_pk_add_f32 v[32:33], v[32:33], v[34:35]
	s_nop 0
	v_pk_add_f32 v[60:61], v[36:37], v[32:33]
	v_mov_b64_e32 v[32:33], v[154:155]
	v_mov_b64_e32 v[34:35], v[156:157]
	v_mov_b64_e32 v[36:37], v[158:159]
	v_mov_b64_e32 v[38:39], v[160:161]
	v_mov_b32_e32 v119, v60
	v_mov_b32_e32 v60, v63
	v_pk_add_f32 v[60:61], v[118:119], v[60:61]
	ds_bpermute_b32 v63, v67, v61
	ds_bpermute_b32 v62, v67, v60
	s_waitcnt lgkmcnt(0)
	v_pk_add_f32 v[60:61], v[60:61], v[62:63]
	ds_bpermute_b32 v63, v69, v61
	ds_bpermute_b32 v62, v69, v60
	s_waitcnt lgkmcnt(0)
	v_pk_add_f32 v[60:61], v[60:61], v[62:63]
	ds_bpermute_b32 v63, v71, v61
	ds_bpermute_b32 v62, v71, v60
	s_waitcnt lgkmcnt(0)
	v_pk_add_f32 v[60:61], v[60:61], v[62:63]
	ds_bpermute_b32 v63, v73, v61
	ds_bpermute_b32 v62, v73, v60
	s_waitcnt lgkmcnt(0)
	v_pk_add_f32 v[60:61], v[60:61], v[62:63]
	ds_bpermute_b32 v63, v123, v61
	ds_bpermute_b32 v62, v123, v60
	s_waitcnt lgkmcnt(0)
	v_pk_add_f32 v[60:61], v[60:61], v[62:63]
	ds_bpermute_b32 v63, v124, v61
	ds_bpermute_b32 v62, v124, v60
	s_waitcnt lgkmcnt(0)
	v_pk_add_f32 v[60:61], v[60:61], v[62:63]
	s_nop 0
	v_pk_fma_f32 v[118:119], v[60:61], s[2:3], v[120:121] op_sel_hi:[1,0,0]
	s_nop 0
	v_mul_f32_e32 v60, 0x4b800000, v119
	v_cmp_gt_f32_e64 s[8:9], s68, v119
	v_cmp_gt_f32_e32 vcc, s68, v118
	s_nop 0
	v_cndmask_b32_e64 v60, v119, v60, s[8:9]
	v_rsq_f32_e32 v60, v60
	s_nop 0
	v_mul_f32_e32 v61, 0x45800000, v60
	v_cndmask_b32_e64 v120, v60, v61, s[8:9]
	v_pk_mul_f32 v[52:53], v[52:53], v[120:121] op_sel_hi:[1,0]
	v_pk_mul_f32 v[50:51], v[50:51], v[120:121] op_sel_hi:[1,0]
	v_pk_mul_f32 v[46:47], v[46:47], v[120:121] op_sel_hi:[1,0]
	v_pk_fma_f32 v[60:61], v[32:33], v[50:51], v[36:37]
	v_pk_fma_f32 v[62:63], v[34:35], v[52:53], v[38:39]
	flat_store_dwordx4 v[40:41], v[60:63]
	v_mov_b64_e32 v[32:33], v[162:163]
	v_mov_b64_e32 v[34:35], v[164:165]
	v_mov_b64_e32 v[36:37], v[166:167]
	v_mov_b64_e32 v[38:39], v[168:169]
	v_pk_mul_f32 v[50:51], v[58:59], v[120:121] op_sel_hi:[1,0]
	v_pk_mul_f32 v[52:53], v[56:57], v[120:121] op_sel_hi:[1,0]
	v_pk_fma_f32 v[58:59], v[34:35], v[50:51], v[38:39]
	v_pk_fma_f32 v[56:57], v[32:33], v[52:53], v[36:37]
	flat_store_dwordx4 v[40:41], v[56:59] offset:1024
	v_mov_b64_e32 v[32:33], v[170:171]
	v_mov_b64_e32 v[34:35], v[172:173]
	v_mov_b64_e32 v[36:37], v[174:175]
	v_mov_b64_e32 v[38:39], v[176:177]
	v_pk_mul_f32 v[50:51], v[116:117], v[120:121] op_sel_hi:[1,0]
	v_pk_mul_f32 v[52:53], v[54:55], v[120:121] op_sel_hi:[1,0]
	v_pk_fma_f32 v[54:55], v[34:35], v[50:51], v[38:39]
	v_pk_fma_f32 v[52:53], v[32:33], v[52:53], v[36:37]
	flat_store_dwordx4 v[40:41], v[52:55] offset:2048
	v_mov_b64_e32 v[32:33], v[178:179]
	v_mov_b64_e32 v[34:35], v[180:181]
	v_mov_b64_e32 v[36:37], v[182:183]
	v_mov_b64_e32 v[38:39], v[184:185]
	v_pk_mul_f32 v[50:51], v[48:49], v[120:121] op_sel_hi:[1,0]
	v_pk_fma_f32 v[48:49], v[32:33], v[46:47], v[36:37]
	v_mul_f32_e32 v32, 0x4b800000, v118
	v_cndmask_b32_e32 v32, v118, v32, vcc
	v_rsq_f32_e32 v32, v32
	v_pk_fma_f32 v[50:51], v[34:35], v[50:51], v[38:39]
	flat_store_dwordx4 v[40:41], v[48:51] offset:3072
	v_mul_f32_e32 v33, 0x45800000, v32
	v_cndmask_b32_e32 v116, v32, v33, vcc
	v_mov_b64_e32 v[32:33], v[154:155]
	v_mov_b64_e32 v[34:35], v[156:157]
	v_mov_b64_e32 v[36:37], v[158:159]
	v_mov_b64_e32 v[38:39], v[160:161]
	v_pk_mul_f32 v[40:41], v[114:115], v[116:117] op_sel_hi:[1,0]
	v_pk_mul_f32 v[44:45], v[44:45], v[116:117] op_sel_hi:[1,0]
	v_pk_mul_f32 v[112:113], v[112:113], v[116:117] op_sel_hi:[1,0]
	v_pk_mul_f32 v[110:111], v[110:111], v[116:117] op_sel_hi:[1,0]
	v_pk_mul_f32 v[108:109], v[108:109], v[116:117] op_sel_hi:[1,0]
	s_andn2_b64 vcc, exec, s[4:5]
	v_pk_fma_f32 v[44:45], v[32:33], v[44:45], v[36:37]
	v_pk_fma_f32 v[46:47], v[34:35], v[40:41], v[38:39]
	flat_store_dwordx4 v[102:103], v[44:47]
	v_mov_b64_e32 v[32:33], v[162:163]
	v_mov_b64_e32 v[34:35], v[164:165]
	v_mov_b64_e32 v[36:37], v[166:167]
	v_mov_b64_e32 v[38:39], v[168:169]
	v_pk_mul_f32 v[40:41], v[42:43], v[116:117] op_sel_hi:[1,0]
	v_pk_fma_f32 v[42:43], v[34:35], v[112:113], v[38:39]
	v_pk_fma_f32 v[40:41], v[32:33], v[40:41], v[36:37]
	flat_store_dwordx4 v[102:103], v[40:43] offset:1024
	v_mov_b64_e32 v[32:33], v[170:171]
	v_mov_b64_e32 v[34:35], v[172:173]
	v_mov_b64_e32 v[36:37], v[174:175]
	v_mov_b64_e32 v[38:39], v[176:177]
	v_pk_fma_f32 v[36:37], v[32:33], v[108:109], v[36:37]
	v_pk_fma_f32 v[38:39], v[34:35], v[110:111], v[38:39]
	flat_store_dwordx4 v[102:103], v[36:39] offset:2048
	v_pk_mul_f32 v[108:109], v[106:107], v[116:117] op_sel_hi:[1,0]
	v_pk_mul_f32 v[110:111], v[104:105], v[116:117] op_sel_hi:[1,0]
	v_mov_b64_e32 v[32:33], v[178:179]
	v_mov_b64_e32 v[34:35], v[180:181]
	v_mov_b64_e32 v[104:105], v[182:183]
	v_mov_b64_e32 v[106:107], v[184:185]
	v_pk_fma_f32 v[32:33], v[32:33], v[110:111], v[104:105]
	v_pk_fma_f32 v[34:35], v[34:35], v[108:109], v[106:107]
	flat_store_dwordx4 v[102:103], v[32:35] offset:3072
	s_cbranch_vccnz .LBB0_50
	v_mad_u64_u32 v[104:105], s[4:5], v88, s7, 0
	v_mad_u64_u32 v[102:103], s[4:5], v92, s7, 0
	v_mad_i32_i24 v105, v89, s7, v105
	v_mad_i32_i24 v103, v93, s7, v103
	v_mad_u64_u32 v[92:93], s[4:5], v98, s7, 0
	v_mad_u64_u32 v[88:89], s[4:5], v100, s7, 0
	v_mad_i32_i24 v93, v99, s7, v93
	v_lshl_add_u64 v[98:99], s[60:61], 0, v[104:105]
	s_mov_b64 s[4:5], 0x6000
	s_mov_b64 s[8:9], 0x7000
	v_mad_i32_i24 v89, v101, s7, v89
	v_lshl_add_u64 v[100:101], v[98:99], 0, s[4:5]
	v_lshl_add_u64 v[98:99], v[98:99], 0, s[8:9]
	v_lshlrev_b32_e32 v152, 2, v66
	v_lshl_add_u64 v[104:105], v[100:101], 0, v[152:153]
	v_lshl_add_u64 v[108:109], v[98:99], 0, v[152:153]
	flat_load_dwordx4 v[104:107], v[104:105]
	s_nop 0
	flat_load_dwordx4 v[108:111], v[108:109]
	s_waitcnt vmcnt(0) lgkmcnt(0)
	v_pk_add_f32 v[110:111], v[110:111], 1.0 op_sel_hi:[1,0]
	v_pk_add_f32 v[108:109], v[108:109], 1.0 op_sel_hi:[1,0]
	v_pk_fma_f32 v[22:23], v[22:23], v[110:111], v[106:107]
	v_pk_fma_f32 v[20:21], v[20:21], v[108:109], v[104:105]
	s_nop 0
	v_cvt_pk_bf16_f32 v20, v20, v21
	v_cvt_pk_bf16_f32 v21, v22, v23
	flat_store_dwordx2 v[84:85], v[20:21]
	v_lshlrev_b32_e32 v20, 2, v68
	v_mov_b32_e32 v21, v153
	v_lshl_add_u64 v[22:23], v[100:101], 0, v[20:21]
	flat_load_dwordx4 v[104:107], v[22:23]
	v_lshl_add_u64 v[22:23], v[98:99], 0, v[20:21]
	flat_load_dwordx4 v[108:111], v[22:23]
	s_waitcnt vmcnt(0) lgkmcnt(0)
	v_pk_add_f32 v[22:23], v[110:111], 1.0 op_sel_hi:[1,0]
	v_pk_add_f32 v[108:109], v[108:109], 1.0 op_sel_hi:[1,0]
	v_pk_fma_f32 v[14:15], v[14:15], v[22:23], v[106:107]
	v_pk_fma_f32 v[12:13], v[12:13], v[108:109], v[104:105]
	s_nop 0
	v_cvt_pk_bf16_f32 v12, v12, v13
	v_cvt_pk_bf16_f32 v13, v14, v15
	flat_store_dwordx2 v[84:85], v[12:13] offset:512
	v_lshlrev_b32_e32 v12, 2, v70
	v_mov_b32_e32 v13, v153
	v_lshl_add_u64 v[14:15], v[100:101], 0, v[12:13]
	flat_load_dwordx4 v[104:107], v[14:15]
	v_lshl_add_u64 v[14:15], v[98:99], 0, v[12:13]
	flat_load_dwordx4 v[108:111], v[14:15]
	s_waitcnt vmcnt(0) lgkmcnt(0)
	v_pk_add_f32 v[14:15], v[110:111], 1.0 op_sel_hi:[1,0]
	v_pk_add_f32 v[22:23], v[108:109], 1.0 op_sel_hi:[1,0]
	v_pk_fma_f32 v[6:7], v[6:7], v[14:15], v[106:107]
	v_pk_fma_f32 v[4:5], v[4:5], v[22:23], v[104:105]
	s_nop 0
	v_cvt_pk_bf16_f32 v4, v4, v5
	v_cvt_pk_bf16_f32 v5, v6, v7
	flat_store_dwordx2 v[84:85], v[4:5] offset:1024
	v_lshlrev_b32_e32 v4, 2, v72
	v_mov_b32_e32 v5, v153
	v_lshl_add_u64 v[6:7], v[100:101], 0, v[4:5]
	flat_load_dwordx4 v[104:107], v[6:7]
	v_lshl_add_u64 v[6:7], v[98:99], 0, v[4:5]
	flat_load_dwordx4 v[98:101], v[6:7]
	s_waitcnt vmcnt(0) lgkmcnt(0)
	v_pk_add_f32 v[6:7], v[100:101], 1.0 op_sel_hi:[1,0]
	v_pk_add_f32 v[14:15], v[98:99], 1.0 op_sel_hi:[1,0]
	v_pk_fma_f32 v[2:3], v[2:3], v[6:7], v[106:107]
	v_pk_fma_f32 v[0:1], v[0:1], v[14:15], v[104:105]
	s_nop 0
	v_cvt_pk_bf16_f32 v0, v0, v1
	v_cvt_pk_bf16_f32 v1, v2, v3
	flat_store_dwordx2 v[84:85], v[0:1] offset:1536
	v_lshl_add_u64 v[0:1], s[60:61], 0, v[102:103]
	v_lshl_add_u64 v[2:3], v[0:1], 0, s[4:5]
	v_lshl_add_u64 v[0:1], v[0:1], 0, s[8:9]
	v_lshl_add_u64 v[6:7], v[2:3], 0, v[152:153]
	flat_load_dwordx4 v[98:101], v[6:7]
	v_lshl_add_u64 v[6:7], v[0:1], 0, v[152:153]
	flat_load_dwordx4 v[102:105], v[6:7]
	s_waitcnt vmcnt(0) lgkmcnt(0)
	v_pk_add_f32 v[6:7], v[104:105], 1.0 op_sel_hi:[1,0]
	v_pk_add_f32 v[14:15], v[102:103], 1.0 op_sel_hi:[1,0]
	v_pk_fma_f32 v[6:7], v[10:11], v[6:7], v[100:101]
	v_pk_fma_f32 v[8:9], v[8:9], v[14:15], v[98:99]
	v_lshl_add_u64 v[10:11], v[82:83], 0, v[90:91]
	v_cvt_pk_bf16_f32 v8, v8, v9
	v_cvt_pk_bf16_f32 v9, v6, v7
	flat_store_dwordx2 v[10:11], v[8:9]
	v_lshl_add_u64 v[6:7], v[2:3], 0, v[20:21]
	v_lshl_add_u64 v[14:15], v[0:1], 0, v[20:21]
	flat_load_dwordx4 v[6:9], v[6:7]
	s_nop 0
	flat_load_dwordx4 v[98:101], v[14:15]
	s_waitcnt vmcnt(0) lgkmcnt(0)
	v_pk_add_f32 v[14:15], v[100:101], 1.0 op_sel_hi:[1,0]
	v_pk_add_f32 v[22:23], v[98:99], 1.0 op_sel_hi:[1,0]
	v_pk_fma_f32 v[8:9], v[30:31], v[14:15], v[8:9]
	v_pk_fma_f32 v[6:7], v[28:29], v[22:23], v[6:7]
	v_lshl_add_u64 v[14:15], v[0:1], 0, v[12:13]
	v_cvt_pk_bf16_f32 v6, v6, v7
	v_cvt_pk_bf16_f32 v7, v8, v9
	flat_store_dwordx2 v[10:11], v[6:7] offset:512
	v_lshl_add_u64 v[6:7], v[2:3], 0, v[12:13]
	flat_load_dwordx4 v[6:9], v[6:7]
	v_lshl_add_u64 v[2:3], v[2:3], 0, v[4:5]
	flat_load_dwordx4 v[28:31], v[14:15]
	v_lshl_add_u64 v[0:1], v[0:1], 0, v[4:5]
	s_waitcnt vmcnt(0) lgkmcnt(0)
	v_pk_add_f32 v[14:15], v[30:31], 1.0 op_sel_hi:[1,0]
	v_pk_add_f32 v[22:23], v[28:29], 1.0 op_sel_hi:[1,0]
	v_pk_fma_f32 v[8:9], v[26:27], v[14:15], v[8:9]
	v_pk_fma_f32 v[6:7], v[24:25], v[22:23], v[6:7]
	s_nop 0
	v_cvt_pk_bf16_f32 v6, v6, v7
	v_cvt_pk_bf16_f32 v7, v8, v9
	flat_store_dwordx2 v[10:11], v[6:7] offset:1024
	flat_load_dwordx4 v[6:9], v[2:3]
	s_nop 0
	flat_load_dwordx4 v[0:3], v[0:1]
	s_waitcnt vmcnt(0) lgkmcnt(0)
	v_pk_add_f32 v[2:3], v[2:3], 1.0 op_sel_hi:[1,0]
	v_pk_add_f32 v[0:1], v[0:1], 1.0 op_sel_hi:[1,0]
	v_pk_fma_f32 v[2:3], v[18:19], v[2:3], v[8:9]
	v_pk_fma_f32 v[0:1], v[16:17], v[0:1], v[6:7]
	v_lshl_add_u64 v[18:19], v[82:83], 0, v[94:95]
	v_cvt_pk_bf16_f32 v0, v0, v1
	v_cvt_pk_bf16_f32 v1, v2, v3
	flat_store_dwordx2 v[10:11], v[0:1] offset:1536
	v_lshl_add_u64 v[0:1], s[60:61], 0, v[92:93]
	v_lshl_add_u64 v[2:3], v[0:1], 0, s[4:5]
	v_lshl_add_u64 v[0:1], v[0:1], 0, s[8:9]
	v_lshl_add_u64 v[6:7], v[2:3], 0, v[152:153]
	v_lshl_add_u64 v[10:11], v[0:1], 0, v[152:153]
	flat_load_dwordx4 v[6:9], v[6:7]
	s_nop 0
	flat_load_dwordx4 v[14:17], v[10:11]
	s_waitcnt vmcnt(0) lgkmcnt(0)
	v_pk_add_f32 v[10:11], v[16:17], 1.0 op_sel_hi:[1,0]
	v_pk_add_f32 v[14:15], v[14:15], 1.0 op_sel_hi:[1,0]
	v_pk_fma_f32 v[8:9], v[62:63], v[10:11], v[8:9]
	v_pk_fma_f32 v[6:7], v[60:61], v[14:15], v[6:7]
	v_lshl_add_u64 v[10:11], v[82:83], 0, v[96:97]
	v_cvt_pk_bf16_f32 v6, v6, v7
	v_cvt_pk_bf16_f32 v7, v8, v9
	flat_store_dwordx2 v[10:11], v[6:7]
	v_lshl_add_u64 v[6:7], v[2:3], 0, v[20:21]
	v_lshl_add_u64 v[14:15], v[0:1], 0, v[20:21]
	flat_load_dwordx4 v[6:9], v[6:7]
	s_nop 0
	flat_load_dwordx4 v[14:17], v[14:15]
	s_waitcnt vmcnt(0) lgkmcnt(0)
	v_pk_add_f32 v[16:17], v[16:17], 1.0 op_sel_hi:[1,0]
	v_pk_add_f32 v[14:15], v[14:15], 1.0 op_sel_hi:[1,0]
	v_pk_fma_f32 v[8:9], v[58:59], v[16:17], v[8:9]
	v_pk_fma_f32 v[6:7], v[56:57], v[14:15], v[6:7]
	v_lshl_add_u64 v[14:15], v[0:1], 0, v[12:13]
	v_cvt_pk_bf16_f32 v6, v6, v7
	v_cvt_pk_bf16_f32 v7, v8, v9
	flat_store_dwordx2 v[10:11], v[6:7] offset:512
	v_lshl_add_u64 v[6:7], v[2:3], 0, v[12:13]
	flat_load_dwordx4 v[6:9], v[6:7]
	v_lshl_add_u64 v[2:3], v[2:3], 0, v[4:5]
	flat_load_dwordx4 v[14:17], v[14:15]
	v_lshl_add_u64 v[0:1], v[0:1], 0, v[4:5]
	s_waitcnt vmcnt(0) lgkmcnt(0)
	v_pk_add_f32 v[16:17], v[16:17], 1.0 op_sel_hi:[1,0]
	v_pk_add_f32 v[14:15], v[14:15], 1.0 op_sel_hi:[1,0]
	v_pk_fma_f32 v[8:9], v[54:55], v[16:17], v[8:9]
	v_pk_fma_f32 v[6:7], v[52:53], v[14:15], v[6:7]
	s_nop 0
	v_cvt_pk_bf16_f32 v6, v6, v7
	v_cvt_pk_bf16_f32 v7, v8, v9
	flat_store_dwordx2 v[10:11], v[6:7] offset:1024
	flat_load_dwordx4 v[6:9], v[2:3]
	s_nop 0
	flat_load_dwordx4 v[0:3], v[0:1]
	s_waitcnt vmcnt(0) lgkmcnt(0)
	v_pk_add_f32 v[2:3], v[2:3], 1.0 op_sel_hi:[1,0]
	v_pk_add_f32 v[0:1], v[0:1], 1.0 op_sel_hi:[1,0]
	v_pk_fma_f32 v[2:3], v[50:51], v[2:3], v[8:9]
	v_pk_fma_f32 v[0:1], v[48:49], v[0:1], v[6:7]
	s_nop 0
	v_cvt_pk_bf16_f32 v0, v0, v1
	v_cvt_pk_bf16_f32 v1, v2, v3
	flat_store_dwordx2 v[10:11], v[0:1] offset:1536
	v_lshl_add_u64 v[0:1], s[60:61], 0, v[88:89]
	v_lshl_add_u64 v[2:3], v[0:1], 0, s[4:5]
	v_lshl_add_u64 v[0:1], v[0:1], 0, s[8:9]
	v_lshl_add_u64 v[6:7], v[2:3], 0, v[152:153]
	v_lshl_add_u64 v[10:11], v[0:1], 0, v[152:153]
	flat_load_dwordx4 v[6:9], v[6:7]
	s_nop 0
	flat_load_dwordx4 v[14:17], v[10:11]
	s_waitcnt vmcnt(0) lgkmcnt(0)
	v_pk_add_f32 v[10:11], v[16:17], 1.0 op_sel_hi:[1,0]
	v_pk_add_f32 v[14:15], v[14:15], 1.0 op_sel_hi:[1,0]
	v_pk_fma_f32 v[8:9], v[46:47], v[10:11], v[8:9]
	v_pk_fma_f32 v[6:7], v[44:45], v[14:15], v[6:7]
	v_lshl_add_u64 v[10:11], v[0:1], 0, v[20:21]
	v_cvt_pk_bf16_f32 v6, v6, v7
	v_cvt_pk_bf16_f32 v7, v8, v9
	flat_store_dwordx2 v[18:19], v[6:7]
	v_lshl_add_u64 v[6:7], v[2:3], 0, v[20:21]
	flat_load_dwordx4 v[6:9], v[6:7]
	s_nop 0
	flat_load_dwordx4 v[14:17], v[10:11]
	s_waitcnt vmcnt(0) lgkmcnt(0)
	v_pk_add_f32 v[10:11], v[16:17], 1.0 op_sel_hi:[1,0]
	v_pk_add_f32 v[14:15], v[14:15], 1.0 op_sel_hi:[1,0]
	v_pk_fma_f32 v[8:9], v[42:43], v[10:11], v[8:9]
	v_pk_fma_f32 v[6:7], v[40:41], v[14:15], v[6:7]
	v_lshl_add_u64 v[10:11], v[0:1], 0, v[12:13]
	v_cvt_pk_bf16_f32 v6, v6, v7
	v_cvt_pk_bf16_f32 v7, v8, v9
	flat_store_dwordx2 v[18:19], v[6:7] offset:512
	v_lshl_add_u64 v[6:7], v[2:3], 0, v[12:13]
	flat_load_dwordx4 v[6:9], v[6:7]
	v_lshl_add_u64 v[2:3], v[2:3], 0, v[4:5]
	flat_load_dwordx4 v[10:13], v[10:11]
	v_lshl_add_u64 v[0:1], v[0:1], 0, v[4:5]
	s_waitcnt vmcnt(0) lgkmcnt(0)
	v_pk_add_f32 v[12:13], v[12:13], 1.0 op_sel_hi:[1,0]
	v_pk_add_f32 v[10:11], v[10:11], 1.0 op_sel_hi:[1,0]
	v_pk_fma_f32 v[8:9], v[38:39], v[12:13], v[8:9]
	v_pk_fma_f32 v[6:7], v[36:37], v[10:11], v[6:7]
	s_nop 0
	v_cvt_pk_bf16_f32 v6, v6, v7
	v_cvt_pk_bf16_f32 v7, v8, v9
	flat_store_dwordx2 v[18:19], v[6:7] offset:1024
	flat_load_dwordx4 v[6:9], v[2:3]
	s_nop 0
	flat_load_dwordx4 v[0:3], v[0:1]
	s_waitcnt vmcnt(0) lgkmcnt(0)
	v_pk_add_f32 v[2:3], v[2:3], 1.0 op_sel_hi:[1,0]
	v_pk_add_f32 v[0:1], v[0:1], 1.0 op_sel_hi:[1,0]
	v_pk_fma_f32 v[2:3], v[34:35], v[2:3], v[8:9]
	v_pk_fma_f32 v[0:1], v[32:33], v[0:1], v[6:7]
	s_nop 0
	v_cvt_pk_bf16_f32 v0, v0, v1
	v_cvt_pk_bf16_f32 v1, v2, v3
	flat_store_dwordx2 v[18:19], v[0:1] offset:1536
	s_branch .LBB0_50

.LBB0_61:
	v_writelane_b32 v255, s14, 6
	s_andn2_b64 vcc, exec, s[8:9]
	s_nop 0
	v_writelane_b32 v255, s15, 7
	s_cbranch_vccnz .LBB0_116
	v_writelane_b32 v255, s92, 8
	v_readlane_b32 s4, v251, 27
	v_readlane_b32 s5, v251, 28
	v_writelane_b32 v255, s93, 9
	v_writelane_b32 v255, s63, 10
	s_andn2_b64 vcc, exec, s[4:5]
	s_cbranch_vccnz .LBB0_102
	s_add_u32 s4, s18, 0xc700000
	s_addc_u32 s5, s19, 0
	v_writelane_b32 v255, s4, 11
	s_mov_b32 s92, s62
	s_mov_b32 s63, s67
	v_writelane_b32 v255, s5, 12
	s_add_u32 s4, s18, 0xef00000
	s_addc_u32 s5, s19, 0
	v_writelane_b32 v255, s4, 13
	s_mov_b32 s43, s71
	s_nop 0
	v_writelane_b32 v255, s5, 14
	s_cmpk_gt_i32 s92, 0x7f
	s_cbranch_scc1 .Lr2map_lat
	s_and_b32 s4, s92, 7
	s_lshl_b32 s4, s4, 1
	s_bfe_u32 s5, s92, 0x10003
	s_andn2_b32 s92, s92, 15
	s_or_b32 s92, s92, s4
	s_or_b32 s92, s92, s5
	s_branch .Lr2map_done
.Lr2map_lat:
	s_and_b32 s4, s92, 7
	s_lshl_b32 s4, s4, 3
	s_bfe_u32 s5, s92, 0x30003
	s_andn2_b32 s92, s92, 63
	s_or_b32 s92, s92, s4
	s_or_b32 s92, s92, s5
.Lr2map_done:
	s_branch .LBB0_65
.LBB0_64:
	s_add_i32 s92, s92, s34
	s_cmpk_gt_i32 s92, 0xff
	v_readlane_b32 s35, v254, 9
	v_mov_b32_e32 v138, v231
	v_mov_b32_e32 v244, v208
	v_mov_b32_e32 v245, v222
	s_waitcnt lgkmcnt(0)
	s_barrier
	s_cbranch_scc1 .LBB0_102
